# stack32 with the seam-4 handshake restructured: election atomic, panel adds and the first poll loads issued together (one round trip less before the first check)
# baseline (speedup 1.0000x reference)
.LBB0_706:
	s_cmp_gt_i32 s89, 5
	v_readlane_b32 s0, v246, 0
	s_cselect_b64 s[2:3], -1, 0
	v_readlane_b32 s1, v246, 1
	s_and_b64 s[0:1], s[0:1], s[2:3]
	s_andn2_b64 vcc, exec, s[0:1]
	s_cbranch_vccnz .LBB0_760
	s_waitcnt vmcnt(0)
	s_waitcnt vmcnt(0)
	s_barrier
	s_and_saveexec_b64 s[4:5], s[84:85]
	s_cbranch_execz .LBB0_759
	s_cmp_lg_u32 s79, 0x100
	s_cbranch_scc1 .Ldf4_full
	s_and_b32 s0, s78, 7
	s_lshl_b32 s0, s0, 5
	s_lshr_b32 s1, s78, 3
	s_add_i32 s0, s0, s1
	s_lshr_b32 s1, s0, 6
	s_lshl_b32 s1, s1, 3
	s_and_b32 s6, s0, 15
	s_lshr_b32 s7, s6, 2
	s_add_i32 s7, s7, s1
	s_sub_i32 s6, 31, s6
	s_lshr_b32 s6, s6, 2
	s_add_i32 s6, s6, s1
	s_and_b32 s98, s0, 7
	s_add_i32 s98, s98, s1
	s_lshl_b32 s6, s6, 8
	s_add_i32 s6, s6, 0xe000
	s_lshl_b32 s7, s7, 8
	s_add_i32 s7, s7, 0xe000
	s_lshl_b32 s98, s98, 8
	s_add_i32 s98, s98, 0xe000
	s_lshl_b32 s99, s82, 8
	s_add_i32 s99, s99, 0xb080
	v_mov_b32_e32 v5, s99
	v_mov_b32_e32 v3, 1
	global_atomic_add v6, v5, v3, s[76:77] sc0
	v_mov_b32_e32 v2, s6
	global_atomic_add v2, v3, s[76:77]
	v_mov_b32_e32 v4, s7
	global_atomic_add v4, v3, s[76:77]
	v_mov_b32_e32 v2, s98
	v_mov_b32_e32 v5, 0xa080
	global_load_dword v4, v2, s[76:77] sc1
	global_load_dword v7, v5, s[76:77] sc1
	v_mov_b32_e32 v8, 0x23e20
	ds_read_b32 v9, v8
	ds_read_b32 v10, v8 offset:4
	s_waitcnt vmcnt(0) lgkmcnt(0)
	s_nop 0
	v_readfirstlane_b32 s99, v6
	v_readfirstlane_b32 s100, v10
	v_readfirstlane_b32 s0, v4
	v_readfirstlane_b32 s1, v7
	s_cmp_lg_u32 s99, 0
	s_cbranch_scc1 .Ldf4_chk
	v_readfirstlane_b32 s99, v9
	s_lshl_b32 s1, s82, 8
	s_add_i32 s1, s1, 0xb000
	v_mov_b32_e32 v8, s1
	s_mov_b32 s101, 0
.Ldf4p_l:
	global_load_dword v6, v8, s[76:77] sc1
	s_waitcnt vmcnt(0)
	v_readfirstlane_b32 s1, v6
	s_cmp_ge_u32 s1, s99
	s_cbranch_scc1 .Ldf4p_g
	s_sleep 1
	s_add_i32 s101, s101, 1
	s_cmp_lt_u32 s101, 0x100000
	s_cbranch_scc1 .Ldf4p_l
.Ldf4p_g:
	buffer_wbl2 sc1
	s_waitcnt vmcnt(0)
	global_atomic_add v5, v3, s[76:77]
	s_branch .Ldf4_poll
.Ldf4_chk:
	s_cmp_ge_u32 s0, 16
	s_cselect_b32 s0, 1, 0
	s_cmp_ge_u32 s1, s100
	s_cselect_b32 s1, 1, 0
	s_and_b32 s0, s0, s1
	s_cmp_lg_u32 s0, 0
	s_cbranch_scc1 .Ldf4_g

.Ldf4_l:
	global_load_dword v4, v2, s[76:77] sc1
	global_load_dword v7, v5, s[76:77] sc1
	s_waitcnt vmcnt(0)
	v_readfirstlane_b32 s0, v4
	v_readfirstlane_b32 s1, v7
	s_cmp_ge_u32 s0, 16
	s_cselect_b32 s0, 1, 0
	s_cmp_ge_u32 s1, s100
	s_cselect_b32 s1, 1, 0
	s_and_b32 s0, s0, s1
	s_cmp_lg_u32 s0, 0
	s_cbranch_scc1 .Ldf4_g
	s_sleep 1
	s_add_i32 s101, s101, 1
	s_cmp_lt_u32 s101, 0x100000
	s_cbranch_scc1 .Ldf4_l
